# sample-row GEMMs hand-written with K-split over all WGs: out-proj x2, FFN-down x2, FFN gate/up x2 (fused silu*u), input projection
# speedup vs baseline: 1.0482x; 1.0133x over previous
;     DI void elem(int row, int col, const f32x4 v) const { u32x2 w; w.x = pk2(v[0], v[1]); w.y = pk2(v[2], v[3]); *(u32x2*)(y + (size_t)row * 1024 + col) = w; }
; DI f32x4 mini_acc(const bf16_t* Arow, const bf16_t* Brow, int K) {
;     f32x4 acc = (f32x4){0.f, 0.f, 0.f, 0.f};
;     int k0 = 0;
;     for (; k0 + 512 <= K; k0 += 512) { bf16x8 a[16], b[16];
; #pragma unroll
;         for (int e = 0; e < 16; ++e) { a[e] = *(const bf16x8*)(Arow + k0 + 32 * e); b[e] = *(const bf16x8*)(Brow + k0 + 32 * e); }
; #pragma unroll
;         for (int e = 0; e < 16; ++e) acc = __builtin_amdgcn_mfma_f32_16x16x32_bf16(b[e], a[e], acc, 0, 0, 0); }
; template <class Epi>
; DI void mini_gemm(const bf16_t* A, int lda, const bf16_t* Bt, int ldb, int K, int N, int acol_per_256, const Epi& E, int bx, int G, int wave, int lane) {
;     const int fr = lane & 15, fq = lane >> 4; const int row = NP + 16 * wave + fr;
;     for (int q = bx; q < N / 16; q += G) {
;         const bf16_t* Arow = A + (size_t)row * lda + ((16 * q) >> 8) * acol_per_256 + 8 * fq;
;         const bf16_t* Brow = Bt + (size_t)(16 * q + fr) * ldb + 8 * fq;
;         const f32x4 acc = mini_acc(Arow, Brow, K);
;         E.elem(row, 16 * q + 4 * fq, acc); }
; }
.LBB0_282:
	s_cmp_lg_u32 s78, 0x100
	s_cbranch_scc1 .Lp1_old_p1
	v_mbcnt_lo_u32_b32 v0, -1, 0
	v_mbcnt_hi_u32_b32 v0, -1, v0
	s_lshr_b32 s4, s84, 6
	s_lshr_b32 s32, s87, 2
	v_and_b32_e32 v1, 15, v0
	v_lshrrev_b32_e32 v2, 4, v0
	s_lshl_b32 s4, s4, 1
	s_add_i32 s4, s4, s32
	s_lshl_b32 s4, s4, 4
	v_add_u32_e32 v5, s4, v1
	v_add_u32_e32 v3, 0x8000, v5
	s_and_b32 s3, s84, 63
	s_lshl_b32 s5, s3, 4
	v_add_u32_e32 v4, s5, v1
	s_and_b32 s32, s87, 3
	s_mul_i32 s32, s32, 0x200
	v_lshl_add_u32 v6, v2, 4, s32
	v_mov_b32_e32 v7, 0
	s_add_u32 s98, s90, 0x4400000
	s_addc_u32 s99, s91, 0
	s_movk_i32 s2, 0x800
	v_lshl_add_u64 v[8:9], s[98:99], 0, v[6:7]
	v_lshl_add_u64 v[10:11], s[90:91], 0, v[6:7]
	v_mad_u64_u32 v[8:9], vcc, v3, s2, v[8:9]
	v_mad_u64_u32 v[10:11], vcc, v4, s2, v[10:11]
	global_load_dwordx4 v[20:23], v[8:9], off
	global_load_dwordx4 v[52:55], v[10:11], off
	global_load_dwordx4 v[24:27], v[8:9], off offset:64
	global_load_dwordx4 v[56:59], v[10:11], off offset:64
	global_load_dwordx4 v[28:31], v[8:9], off offset:128
	global_load_dwordx4 v[60:63], v[10:11], off offset:128
	global_load_dwordx4 v[32:35], v[8:9], off offset:192
	global_load_dwordx4 v[64:67], v[10:11], off offset:192
	global_load_dwordx4 v[36:39], v[8:9], off offset:256
	global_load_dwordx4 v[68:71], v[10:11], off offset:256
	global_load_dwordx4 v[40:43], v[8:9], off offset:320
	global_load_dwordx4 v[72:75], v[10:11], off offset:320
	global_load_dwordx4 v[44:47], v[8:9], off offset:384
	global_load_dwordx4 v[76:79], v[10:11], off offset:384
	global_load_dwordx4 v[48:51], v[8:9], off offset:448
	global_load_dwordx4 v[80:83], v[10:11], off offset:448
	s_lshl_b32 s4, s87, 10
	v_lshl_add_u32 v12, v0, 4, s4
	s_and_b32 s4, s3, 31
	s_lshl_b32 s4, s4, 6
	v_lshl_add_u32 v14, v2, 4, s4
	v_mov_b32_e32 v15, 0
	s_cmp_lt_u32 s3, 32
	s_cselect_b32 s4, 0x1d800000, 0x0
	s_cselect_b32 s5, 0, 0x3c00000
	s_add_i32 s4, s4, s5
	s_add_u32 s6, s90, s4
	s_addc_u32 s7, s91, 0
	v_lshl_add_u64 v[100:101], s[6:7], 0, v[14:15]
	v_mad_u64_u32 v[100:101], vcc, v5, s2, v[100:101]
	s_waitcnt vmcnt(14)
	v_mfma_f32_16x16x32_bf16 v[84:87], v[52:55], v[20:23], 0
	s_waitcnt vmcnt(12)
	v_mfma_f32_16x16x32_bf16 v[84:87], v[56:59], v[24:27], v[84:87]
	s_waitcnt vmcnt(10)
	v_mfma_f32_16x16x32_bf16 v[84:87], v[60:63], v[28:31], v[84:87]
	s_waitcnt vmcnt(8)
	v_mfma_f32_16x16x32_bf16 v[84:87], v[64:67], v[32:35], v[84:87]
	s_waitcnt vmcnt(6)
	v_mfma_f32_16x16x32_bf16 v[84:87], v[68:71], v[36:39], v[84:87]
	s_waitcnt vmcnt(4)
	v_mfma_f32_16x16x32_bf16 v[84:87], v[72:75], v[40:43], v[84:87]
	s_waitcnt vmcnt(2)
	v_mfma_f32_16x16x32_bf16 v[84:87], v[76:79], v[44:47], v[84:87]
	s_waitcnt vmcnt(0)
	v_mfma_f32_16x16x32_bf16 v[84:87], v[80:83], v[48:51], v[84:87]
	s_nop 7
	s_nop 1
	ds_write_b128 v12, v[84:87]
	s_waitcnt lgkmcnt(0)
	s_barrier
	s_and_b32 s32, s87, 3
	s_cmp_lg_u32 s32, 0
	s_cbranch_scc1 .Lp1_done_p1
	ds_read_b128 v[88:91], v12 offset:1024
	ds_read_b128 v[92:95], v12 offset:2048
	ds_read_b128 v[96:99], v12 offset:3072
	s_waitcnt lgkmcnt(0)
	v_pk_add_f32 v[84:85], v[84:85], v[88:89]
	v_pk_add_f32 v[92:93], v[92:93], v[96:97]
	v_pk_add_f32 v[86:87], v[86:87], v[90:91]
	v_pk_add_f32 v[94:95], v[94:95], v[98:99]
	v_pk_add_f32 v[84:85], v[84:85], v[92:93]
	v_pk_add_f32 v[86:87], v[86:87], v[94:95]
	s_nop 0
	global_store_dwordx4 v[100:101], v[84:87], off
.Lp1_done_p1:
	s_branch .LBB0_289
.Lp1_old_p1:
	s_cmp_gt_i32 s84, 63
	s_cbranch_scc1 .LBB0_289
	s_lshl_b32 s2, s87, 4
	v_and_b32_e32 v16, 15, v154
	s_add_i32 s2, s2, 0x8000
	v_ashrrev_i32_e32 v10, 4, v154
	v_or_b32_e32 v4, s2, v16
	v_mov_b32_e32 v5, 0
	v_lshlrev_b32_e32 v6, 3, v10
	v_lshlrev_b64 v[0:1], 11, v[4:5]
	v_ashrrev_i32_e32 v7, 31, v6
	v_lshl_add_u64 v[2:3], s[12:13], 0, v[0:1]
	v_lshlrev_b64 v[8:9], 1, v[6:7]
	v_add_u32_e32 v4, 0xffff8000, v4
	v_lshl_add_u64 v[6:7], v[2:3], 0, v[8:9]
	v_lshlrev_b64 v[2:3], 11, v[4:5]
	v_lshl_add_u64 v[8:9], s[90:91], 0, v[8:9]
	v_lshlrev_b32_e32 v17, 2, v10
	v_lshl_add_u64 v[10:11], s[10:11], 0, v[2:3]
	v_lshl_add_u64 v[12:13], s[8:9], 0, v[0:1]
	s_lshl_b32 s2, s84, 4
	s_lshl_b32 s3, s78, 4
	s_movk_i32 s6, 0x1ff
	s_mov_b32 s7, s84
	s_branch .LBB0_285

;     DI void elem(int row, int col, const f32x4 v) const { u32x2 w; w.x = pk2(v[0], v[1]); w.y = pk2(v[2], v[3]); *(u32x2*)(y + (size_t)row * 1024 + col) = w; }
; DI void mini_acc2(const bf16_t* Arow, const bf16_t* Bg, const bf16_t* Bu, int K, f32x4& ga, f32x4& ua) {
;     ga = (f32x4){0.f, 0.f, 0.f, 0.f}; ua = ga;
;     for (int k0 = 0; k0 < K; k0 += 256) { bf16x8 a[8], g[8], u[8];
; #pragma unroll
;         for (int e = 0; e < 8; ++e) { a[e] = *(const bf16x8*)(Arow + k0 + 32 * e); g[e] = *(const bf16x8*)(Bg + k0 + 32 * e); u[e] = *(const bf16x8*)(Bu + k0 + 32 * e); }
; #pragma unroll
;         for (int e = 0; e < 8; ++e) { ga = __builtin_amdgcn_mfma_f32_16x16x32_bf16(g[e], a[e], ga, 0, 0, 0); ua = __builtin_amdgcn_mfma_f32_16x16x32_bf16(u[e], a[e], ua, 0, 0, 0); } }
; }
; template <class Epi>
; DI void mini_gemm(const bf16_t* A, int lda, const bf16_t* Bt, int ldb, int K, int N, int acol_per_256, const Epi& E, int bx, int G, int wave, int lane) {
;     const int fr = lane & 15, fq = lane >> 4; const int row = NP + 16 * wave + fr;
;     for (int q = bx; q < N / 16; q += G) {
;         const bf16_t* Arow = A + (size_t)row * lda + ((16 * q) >> 8) * acol_per_256 + 8 * fq;
;         const bf16_t* Brow = Bt + (size_t)(16 * q + fr) * ldb + 8 * fq;
;         const f32x4 acc = mini_acc(Arow, Brow, K);
;         E.elem(row, 16 * q + 4 * fq, acc); }
; }
; DI void mini_gemm_gu(const bf16_t* A, const bf16_t* Bt, const EpiGU& E, int bx, int G, int wave, int lane) {
;     const int fr = lane & 15, fq = lane >> 4; const int row = NP + 16 * wave + fr;
;     for (int q = bx; q < FF / 16; q += G) { const int hcol = 16 * q; const int brow = (hcol >> 7) * 256 + (hcol & 127) + fr;
;         const bf16_t* Arow = A + (size_t)row * DM + 8 * fq;
;         f32x4 ga, ua; mini_acc2(Arow, Bt + (size_t)brow * DM + 8 * fq, Bt + (size_t)(brow + 128) * DM + 8 * fq, DM, ga, ua);
;         E.elem2(row, hcol + 4 * fq, ga, ua); }
; }
.LBB0_1061:
	s_cmp_lg_u32 s78, 0x100
	s_cbranch_scc1 .Lgu_old_p8
	v_mbcnt_lo_u32_b32 v0, -1, 0
	v_mbcnt_hi_u32_b32 v0, -1, v0
	v_and_b32_e32 v1, 15, v0
	v_lshrrev_b32_e32 v2, 4, v0
	s_and_b32 s32, s87, 3
	s_lshl_b32 s32, s32, 9
	v_lshl_add_u32 v6, v2, 4, s32
	v_mov_b32_e32 v7, 0
	s_add_u32 s98, s90, 0x4400000
	s_addc_u32 s99, s91, 0
	s_add_u32 s100, s90, 0xd00000
	s_addc_u32 s101, s91, 0
	s_movk_i32 s2, 0x800
	s_lshl_b32 s1, s87, 10
	v_lshl_add_u32 v16, v0, 4, s1
	v_lshl_add_u64 v[14:15], s[98:99], 0, v[6:7]
	v_lshl_add_u64 v[18:19], s[100:101], 0, v[6:7]
	s_add_i32 s3, s84, 0x0
	s_and_b32 s0, s3, 7
	s_lshr_b32 s1, s3, 5
	s_lshl_b32 s1, s1, 3
	s_add_i32 s0, s0, s1
	s_bfe_u32 s1, s3, 0x20003
	s_lshl_b32 s1, s1, 1
	s_lshr_b32 s4, s87, 2
	s_add_i32 s1, s1, s4
	s_lshl_b32 s1, s1, 4
	s_add_i32 s1, s1, 0x8000
	v_add_u32_e32 v3, s1, v1
	s_lshr_b32 s4, s0, 3
	s_lshl_b32 s4, s4, 8
	s_and_b32 s5, s0, 7
	s_lshl_b32 s5, s5, 4
	s_add_i32 s4, s4, s5
	v_add_u32_e32 v4, s4, v1
	v_mad_u64_u32 v[8:9], vcc, v3, s2, v[14:15]
	v_mad_u64_u32 v[10:11], vcc, v4, s2, v[18:19]
	v_add_co_u32_e32 v12, vcc, 0x40000, v10
	s_nop 1
	v_addc_co_u32_e32 v13, vcc, 0, v11, vcc
	global_load_dwordx4 v[20:23], v[8:9], off
	global_load_dwordx4 v[52:55], v[10:11], off
	global_load_dwordx4 v[84:87], v[12:13], off
	global_load_dwordx4 v[24:27], v[8:9], off offset:64
	global_load_dwordx4 v[56:59], v[10:11], off offset:64
	global_load_dwordx4 v[88:91], v[12:13], off offset:64
	global_load_dwordx4 v[28:31], v[8:9], off offset:128
	global_load_dwordx4 v[60:63], v[10:11], off offset:128
	global_load_dwordx4 v[92:95], v[12:13], off offset:128
	global_load_dwordx4 v[32:35], v[8:9], off offset:192
	global_load_dwordx4 v[64:67], v[10:11], off offset:192
	global_load_dwordx4 v[96:99], v[12:13], off offset:192
	global_load_dwordx4 v[36:39], v[8:9], off offset:256
	global_load_dwordx4 v[68:71], v[10:11], off offset:256
	global_load_dwordx4 v[100:103], v[12:13], off offset:256
	global_load_dwordx4 v[40:43], v[8:9], off offset:320
	global_load_dwordx4 v[72:75], v[10:11], off offset:320
	global_load_dwordx4 v[104:107], v[12:13], off offset:320
	global_load_dwordx4 v[44:47], v[8:9], off offset:384
	global_load_dwordx4 v[76:79], v[10:11], off offset:384
	global_load_dwordx4 v[108:111], v[12:13], off offset:384
	global_load_dwordx4 v[48:51], v[8:9], off offset:448
	global_load_dwordx4 v[80:83], v[10:11], off offset:448
	global_load_dwordx4 v[112:115], v[12:13], off offset:448
	v_lshlrev_b32_e32 v192, 3, v2
	s_lshl_b32 s1, s0, 5
	v_add_u32_e32 v192, s1, v192
	v_mov_b32_e32 v193, 0
	s_add_u32 s4, s90, 0x14800000
	s_addc_u32 s5, s91, 0
	v_lshl_add_u64 v[192:193], s[4:5], 0, v[192:193]
	s_movk_i32 s1, 0x1600
	v_mad_u64_u32 v[192:193], vcc, v3, s1, v[192:193]
	s_waitcnt vmcnt(21)
	v_mfma_f32_16x16x32_bf16 v[120:123], v[52:55], v[20:23], 0
	v_mfma_f32_16x16x32_bf16 v[124:127], v[84:87], v[20:23], 0
	s_waitcnt vmcnt(18)
	v_mfma_f32_16x16x32_bf16 v[120:123], v[56:59], v[24:27], v[120:123]
	v_mfma_f32_16x16x32_bf16 v[124:127], v[88:91], v[24:27], v[124:127]
	s_waitcnt vmcnt(15)
	v_mfma_f32_16x16x32_bf16 v[120:123], v[60:63], v[28:31], v[120:123]
	v_mfma_f32_16x16x32_bf16 v[124:127], v[92:95], v[28:31], v[124:127]
	s_waitcnt vmcnt(12)
	v_mfma_f32_16x16x32_bf16 v[120:123], v[64:67], v[32:35], v[120:123]
	v_mfma_f32_16x16x32_bf16 v[124:127], v[96:99], v[32:35], v[124:127]
	s_waitcnt vmcnt(9)
	v_mfma_f32_16x16x32_bf16 v[120:123], v[68:71], v[36:39], v[120:123]
	v_mfma_f32_16x16x32_bf16 v[124:127], v[100:103], v[36:39], v[124:127]
	s_waitcnt vmcnt(6)
	v_mfma_f32_16x16x32_bf16 v[120:123], v[72:75], v[40:43], v[120:123]
	v_mfma_f32_16x16x32_bf16 v[124:127], v[104:107], v[40:43], v[124:127]
	s_waitcnt vmcnt(3)
	v_mfma_f32_16x16x32_bf16 v[120:123], v[76:79], v[44:47], v[120:123]
	v_mfma_f32_16x16x32_bf16 v[124:127], v[108:111], v[44:47], v[124:127]
	s_waitcnt vmcnt(0)
	v_mfma_f32_16x16x32_bf16 v[120:123], v[80:83], v[48:51], v[120:123]
	v_mfma_f32_16x16x32_bf16 v[124:127], v[112:115], v[48:51], v[124:127]
	s_add_i32 s3, s84, 0x100
	s_and_b32 s0, s3, 7
	s_lshr_b32 s1, s3, 5
	s_lshl_b32 s1, s1, 3
	s_add_i32 s0, s0, s1
	s_bfe_u32 s1, s3, 0x20003
	s_lshl_b32 s1, s1, 1
	s_lshr_b32 s4, s87, 2
	s_add_i32 s1, s1, s4
	s_lshl_b32 s1, s1, 4
	s_add_i32 s1, s1, 0x8000
	v_add_u32_e32 v3, s1, v1
	s_lshr_b32 s4, s0, 3
	s_lshl_b32 s4, s4, 8
	s_and_b32 s5, s0, 7
	s_lshl_b32 s5, s5, 4
	s_add_i32 s4, s4, s5
	v_add_u32_e32 v4, s4, v1
	v_mad_u64_u32 v[8:9], vcc, v3, s2, v[14:15]
	v_mad_u64_u32 v[10:11], vcc, v4, s2, v[18:19]
	v_add_co_u32_e32 v12, vcc, 0x40000, v10
	s_nop 1
	v_addc_co_u32_e32 v13, vcc, 0, v11, vcc
	global_load_dwordx4 v[20:23], v[8:9], off
	global_load_dwordx4 v[52:55], v[10:11], off
	global_load_dwordx4 v[84:87], v[12:13], off
	global_load_dwordx4 v[24:27], v[8:9], off offset:64
	global_load_dwordx4 v[56:59], v[10:11], off offset:64
	global_load_dwordx4 v[88:91], v[12:13], off offset:64
	global_load_dwordx4 v[28:31], v[8:9], off offset:128
	global_load_dwordx4 v[60:63], v[10:11], off offset:128
	global_load_dwordx4 v[92:95], v[12:13], off offset:128
	global_load_dwordx4 v[32:35], v[8:9], off offset:192
	global_load_dwordx4 v[64:67], v[10:11], off offset:192
	global_load_dwordx4 v[96:99], v[12:13], off offset:192
	global_load_dwordx4 v[36:39], v[8:9], off offset:256
	global_load_dwordx4 v[68:71], v[10:11], off offset:256
	global_load_dwordx4 v[100:103], v[12:13], off offset:256
	global_load_dwordx4 v[40:43], v[8:9], off offset:320
	global_load_dwordx4 v[72:75], v[10:11], off offset:320
	global_load_dwordx4 v[104:107], v[12:13], off offset:320
	global_load_dwordx4 v[44:47], v[8:9], off offset:384
	global_load_dwordx4 v[76:79], v[10:11], off offset:384
	global_load_dwordx4 v[108:111], v[12:13], off offset:384
	global_load_dwordx4 v[48:51], v[8:9], off offset:448
	global_load_dwordx4 v[80:83], v[10:11], off offset:448
	global_load_dwordx4 v[112:115], v[12:13], off offset:448
	v_lshlrev_b32_e32 v194, 3, v2
	s_lshl_b32 s1, s0, 5
	v_add_u32_e32 v194, s1, v194
	v_mov_b32_e32 v195, 0
	s_add_u32 s4, s90, 0x14800000
	s_addc_u32 s5, s91, 0
	v_lshl_add_u64 v[194:195], s[4:5], 0, v[194:195]
	s_movk_i32 s1, 0x1600
	v_mad_u64_u32 v[194:195], vcc, v3, s1, v[194:195]
	s_nop 7
	s_nop 1
	ds_write_b128 v16, v[120:123] offset:0
	ds_write_b128 v16, v[124:127] offset:8192
	s_waitcnt lgkmcnt(0)
	s_barrier
; DI float sigmoidf_(float x) { return __builtin_amdgcn_rcpf(1.0f + __builtin_amdgcn_exp2f(-1.4426950408889634f * x)); }
;     DI void elem(int row, int col, const f32x4 v) const { u32x2 w; w.x = pk2(v[0], v[1]); w.y = pk2(v[2], v[3]); *(u32x2*)(y + (size_t)row * 1024 + col) = w; }
;     DI void elem2(int row, int col, const f32x4 a, const f32x4 u) const { u32x2 w; w.x = pk2(a[0] * sigmoidf_(a[0]) * u[0], a[1] * sigmoidf_(a[1]) * u[1]); w.y = pk2(a[2] * sigmoidf_(a[2]) * u[2], a[3] * sigmoidf_(a[3]) * u[3]);
;         *(u32x2*)(hact + (size_t)row * FF + col) = w; }
; DI void mini_acc2(const bf16_t* Arow, const bf16_t* Bg, const bf16_t* Bu, int K, f32x4& ga, f32x4& ua) {
;     ga = (f32x4){0.f, 0.f, 0.f, 0.f}; ua = ga;
;     for (int k0 = 0; k0 < K; k0 += 256) { bf16x8 a[8], g[8], u[8];
; #pragma unroll
;         for (int e = 0; e < 8; ++e) { a[e] = *(const bf16x8*)(Arow + k0 + 32 * e); g[e] = *(const bf16x8*)(Bg + k0 + 32 * e); u[e] = *(const bf16x8*)(Bu + k0 + 32 * e); }
; #pragma unroll
;         for (int e = 0; e < 8; ++e) { ga = __builtin_amdgcn_mfma_f32_16x16x32_bf16(g[e], a[e], ga, 0, 0, 0); ua = __builtin_amdgcn_mfma_f32_16x16x32_bf16(u[e], a[e], ua, 0, 0, 0); } }
; }
; template <class Epi>
; DI void mini_gemm(const bf16_t* A, int lda, const bf16_t* Bt, int ldb, int K, int N, int acol_per_256, const Epi& E, int bx, int G, int wave, int lane) {
;     const int fr = lane & 15, fq = lane >> 4; const int row = NP + 16 * wave + fr;
;     for (int q = bx; q < N / 16; q += G) {
;         const bf16_t* Arow = A + (size_t)row * lda + ((16 * q) >> 8) * acol_per_256 + 8 * fq;
;         const bf16_t* Brow = Bt + (size_t)(16 * q + fr) * ldb + 8 * fq;
;         const f32x4 acc = mini_acc(Arow, Brow, K);
;         E.elem(row, 16 * q + 4 * fq, acc); }
; }
; DI void mini_gemm_gu(const bf16_t* A, const bf16_t* Bt, const EpiGU& E, int bx, int G, int wave, int lane) {
;     const int fr = lane & 15, fq = lane >> 4; const int row = NP + 16 * wave + fr;
;     for (int q = bx; q < FF / 16; q += G) { const int hcol = 16 * q; const int brow = (hcol >> 7) * 256 + (hcol & 127) + fr;
;         const bf16_t* Arow = A + (size_t)row * DM + 8 * fq;
;         f32x4 ga, ua; mini_acc2(Arow, Bt + (size_t)brow * DM + 8 * fq, Bt + (size_t)(brow + 128) * DM + 8 * fq, DM, ga, ua);
;         E.elem2(row, hcol + 4 * fq, ga, ua); }
; }
	s_and_b32 s1, s87, 3
	s_cmp_lg_u32 s1, 0
	s_cbranch_scc1 .Lgu_red_done_p8_0
	ds_read_b128 v[150:153], v16 offset:1024
	ds_read_b128 v[154:157], v16 offset:2048
	ds_read_b128 v[158:161], v16 offset:3072
	ds_read_b128 v[162:165], v16 offset:9216
	ds_read_b128 v[166:169], v16 offset:10240
	ds_read_b128 v[170:173], v16 offset:11264
	s_waitcnt lgkmcnt(0)
	v_pk_add_f32 v[120:121], v[120:121], v[150:151]
	v_pk_add_f32 v[154:155], v[154:155], v[158:159]
	v_pk_add_f32 v[122:123], v[122:123], v[152:153]
	v_pk_add_f32 v[156:157], v[156:157], v[160:161]
	v_pk_add_f32 v[120:121], v[120:121], v[154:155]
	v_pk_add_f32 v[122:123], v[122:123], v[156:157]
	v_pk_add_f32 v[124:125], v[124:125], v[162:163]
	v_pk_add_f32 v[166:167], v[166:167], v[170:171]
	v_pk_add_f32 v[126:127], v[126:127], v[164:165]
	v_pk_add_f32 v[168:169], v[168:169], v[172:173]
	v_pk_add_f32 v[124:125], v[124:125], v[166:167]
	v_pk_add_f32 v[126:127], v[126:127], v[168:169]
	v_mul_f32_e32 v176, 0xbfb8aa3b, v120
	v_mul_f32_e32 v177, 0xbfb8aa3b, v121
	v_mul_f32_e32 v178, 0xbfb8aa3b, v122
	v_mul_f32_e32 v179, 0xbfb8aa3b, v123
	v_exp_f32_e32 v176, v176
	v_exp_f32_e32 v177, v177
	v_exp_f32_e32 v178, v178
	v_exp_f32_e32 v179, v179
	s_nop 0
	v_add_f32_e32 v176, 1.0, v176
	v_add_f32_e32 v177, 1.0, v177
	v_add_f32_e32 v178, 1.0, v178
	v_add_f32_e32 v179, 1.0, v179
	v_rcp_f32_e32 v176, v176
	v_rcp_f32_e32 v177, v177
	v_rcp_f32_e32 v178, v178
	v_rcp_f32_e32 v179, v179
	s_nop 0
	v_mul_f32_e32 v176, v120, v176
	v_mul_f32_e32 v177, v121, v177
	v_mul_f32_e32 v178, v122, v178
	v_mul_f32_e32 v179, v123, v179
	v_mul_f32_e32 v176, v176, v124
	v_mul_f32_e32 v177, v177, v125
	v_mul_f32_e32 v178, v178, v126
	v_mul_f32_e32 v179, v179, v127
	v_cvt_pk_bf16_f32 v180, v176, v177
	v_cvt_pk_bf16_f32 v181, v178, v179
	global_store_dwordx2 v[192:193], v[180:181], off
.Lgu_red_done_p8_0:
	s_waitcnt vmcnt(21)
	v_mfma_f32_16x16x32_bf16 v[128:131], v[52:55], v[20:23], 0
	v_mfma_f32_16x16x32_bf16 v[132:135], v[84:87], v[20:23], 0
	s_waitcnt vmcnt(18)
	v_mfma_f32_16x16x32_bf16 v[128:131], v[56:59], v[24:27], v[128:131]
	v_mfma_f32_16x16x32_bf16 v[132:135], v[88:91], v[24:27], v[132:135]
	s_waitcnt vmcnt(15)
	v_mfma_f32_16x16x32_bf16 v[128:131], v[60:63], v[28:31], v[128:131]
	v_mfma_f32_16x16x32_bf16 v[132:135], v[92:95], v[28:31], v[132:135]
	s_waitcnt vmcnt(12)
	v_mfma_f32_16x16x32_bf16 v[128:131], v[64:67], v[32:35], v[128:131]
	v_mfma_f32_16x16x32_bf16 v[132:135], v[96:99], v[32:35], v[132:135]
	s_waitcnt vmcnt(9)
	v_mfma_f32_16x16x32_bf16 v[128:131], v[68:71], v[36:39], v[128:131]
	v_mfma_f32_16x16x32_bf16 v[132:135], v[100:103], v[36:39], v[132:135]
	s_waitcnt vmcnt(6)
	v_mfma_f32_16x16x32_bf16 v[128:131], v[72:75], v[40:43], v[128:131]
	v_mfma_f32_16x16x32_bf16 v[132:135], v[104:107], v[40:43], v[132:135]
	s_waitcnt vmcnt(3)
	v_mfma_f32_16x16x32_bf16 v[128:131], v[76:79], v[44:47], v[128:131]
	v_mfma_f32_16x16x32_bf16 v[132:135], v[108:111], v[44:47], v[132:135]
	s_waitcnt vmcnt(0)
	v_mfma_f32_16x16x32_bf16 v[128:131], v[80:83], v[48:51], v[128:131]
	v_mfma_f32_16x16x32_bf16 v[132:135], v[112:115], v[48:51], v[132:135]
	s_cmpk_gt_u32 s84, 0xbf
	s_cbranch_scc1 .Lgu_last_p8
	s_add_i32 s3, s84, 0x200
	s_and_b32 s0, s3, 7
	s_lshr_b32 s1, s3, 5
	s_lshl_b32 s1, s1, 3
	s_add_i32 s0, s0, s1
	s_bfe_u32 s1, s3, 0x20003
	s_lshl_b32 s1, s1, 1
	s_lshr_b32 s4, s87, 2
	s_add_i32 s1, s1, s4
	s_lshl_b32 s1, s1, 4
	s_add_i32 s1, s1, 0x8000
	v_add_u32_e32 v3, s1, v1
	s_lshr_b32 s4, s0, 3
	s_lshl_b32 s4, s4, 8
	s_and_b32 s5, s0, 7
	s_lshl_b32 s5, s5, 4
	s_add_i32 s4, s4, s5
	v_add_u32_e32 v4, s4, v1
	v_mad_u64_u32 v[8:9], vcc, v3, s2, v[14:15]
	v_mad_u64_u32 v[10:11], vcc, v4, s2, v[18:19]
	v_add_co_u32_e32 v12, vcc, 0x40000, v10
	s_nop 1
	v_addc_co_u32_e32 v13, vcc, 0, v11, vcc
	global_load_dwordx4 v[20:23], v[8:9], off
	global_load_dwordx4 v[52:55], v[10:11], off
	global_load_dwordx4 v[84:87], v[12:13], off
	global_load_dwordx4 v[24:27], v[8:9], off offset:64
	global_load_dwordx4 v[56:59], v[10:11], off offset:64
	global_load_dwordx4 v[88:91], v[12:13], off offset:64
	global_load_dwordx4 v[28:31], v[8:9], off offset:128
	global_load_dwordx4 v[60:63], v[10:11], off offset:128
	global_load_dwordx4 v[92:95], v[12:13], off offset:128
	global_load_dwordx4 v[32:35], v[8:9], off offset:192
	global_load_dwordx4 v[64:67], v[10:11], off offset:192
	global_load_dwordx4 v[96:99], v[12:13], off offset:192
	global_load_dwordx4 v[36:39], v[8:9], off offset:256
	global_load_dwordx4 v[68:71], v[10:11], off offset:256
	global_load_dwordx4 v[100:103], v[12:13], off offset:256
	global_load_dwordx4 v[40:43], v[8:9], off offset:320
	global_load_dwordx4 v[72:75], v[10:11], off offset:320
	global_load_dwordx4 v[104:107], v[12:13], off offset:320
	global_load_dwordx4 v[44:47], v[8:9], off offset:384
	global_load_dwordx4 v[76:79], v[10:11], off offset:384
	global_load_dwordx4 v[108:111], v[12:13], off offset:384
	global_load_dwordx4 v[48:51], v[8:9], off offset:448
	global_load_dwordx4 v[80:83], v[10:11], off offset:448
	global_load_dwordx4 v[112:115], v[12:13], off offset:448
	v_lshlrev_b32_e32 v196, 3, v2
	s_lshl_b32 s1, s0, 5
	v_add_u32_e32 v196, s1, v196
	v_mov_b32_e32 v197, 0
	s_add_u32 s4, s90, 0x14800000
	s_addc_u32 s5, s91, 0
	v_lshl_add_u64 v[196:197], s[4:5], 0, v[196:197]
	s_movk_i32 s1, 0x1600
	v_mad_u64_u32 v[196:197], vcc, v3, s1, v[196:197]
	s_nop 7
	s_nop 1
	ds_write_b128 v16, v[128:131] offset:16384
	ds_write_b128 v16, v[132:135] offset:24576
	s_waitcnt lgkmcnt(0)
	s_barrier
; DI float sigmoidf_(float x) { return __builtin_amdgcn_rcpf(1.0f + __builtin_amdgcn_exp2f(-1.4426950408889634f * x)); }
;     DI void elem(int row, int col, const f32x4 v) const { u32x2 w; w.x = pk2(v[0], v[1]); w.y = pk2(v[2], v[3]); *(u32x2*)(y + (size_t)row * 1024 + col) = w; }
;     DI void elem2(int row, int col, const f32x4 a, const f32x4 u) const { u32x2 w; w.x = pk2(a[0] * sigmoidf_(a[0]) * u[0], a[1] * sigmoidf_(a[1]) * u[1]); w.y = pk2(a[2] * sigmoidf_(a[2]) * u[2], a[3] * sigmoidf_(a[3]) * u[3]);
;         *(u32x2*)(hact + (size_t)row * FF + col) = w; }
; DI void mini_acc2(const bf16_t* Arow, const bf16_t* Bg, const bf16_t* Bu, int K, f32x4& ga, f32x4& ua) {
;     ga = (f32x4){0.f, 0.f, 0.f, 0.f}; ua = ga;
;     for (int k0 = 0; k0 < K; k0 += 256) { bf16x8 a[8], g[8], u[8];
; #pragma unroll
;         for (int e = 0; e < 8; ++e) { a[e] = *(const bf16x8*)(Arow + k0 + 32 * e); g[e] = *(const bf16x8*)(Bg + k0 + 32 * e); u[e] = *(const bf16x8*)(Bu + k0 + 32 * e); }
; #pragma unroll
;         for (int e = 0; e < 8; ++e) { ga = __builtin_amdgcn_mfma_f32_16x16x32_bf16(g[e], a[e], ga, 0, 0, 0); ua = __builtin_amdgcn_mfma_f32_16x16x32_bf16(u[e], a[e], ua, 0, 0, 0); } }
; }
; template <class Epi>
; DI void mini_gemm(const bf16_t* A, int lda, const bf16_t* Bt, int ldb, int K, int N, int acol_per_256, const Epi& E, int bx, int G, int wave, int lane) {
;     const int fr = lane & 15, fq = lane >> 4; const int row = NP + 16 * wave + fr;
;     for (int q = bx; q < N / 16; q += G) {
;         const bf16_t* Arow = A + (size_t)row * lda + ((16 * q) >> 8) * acol_per_256 + 8 * fq;
;         const bf16_t* Brow = Bt + (size_t)(16 * q + fr) * ldb + 8 * fq;
;         const f32x4 acc = mini_acc(Arow, Brow, K);
;         E.elem(row, 16 * q + 4 * fq, acc); }
; }
; DI void mini_gemm_gu(const bf16_t* A, const bf16_t* Bt, const EpiGU& E, int bx, int G, int wave, int lane) {
;     const int fr = lane & 15, fq = lane >> 4; const int row = NP + 16 * wave + fr;
;     for (int q = bx; q < FF / 16; q += G) { const int hcol = 16 * q; const int brow = (hcol >> 7) * 256 + (hcol & 127) + fr;
;         const bf16_t* Arow = A + (size_t)row * DM + 8 * fq;
;         f32x4 ga, ua; mini_acc2(Arow, Bt + (size_t)brow * DM + 8 * fq, Bt + (size_t)(brow + 128) * DM + 8 * fq, DM, ga, ua);
;         E.elem2(row, hcol + 4 * fq, ga, ua); }
; }
	s_and_b32 s1, s87, 3
	s_cmp_lg_u32 s1, 0
	s_cbranch_scc1 .Lgu_red_done_p8_1
	ds_read_b128 v[150:153], v16 offset:17408
	ds_read_b128 v[154:157], v16 offset:18432
	ds_read_b128 v[158:161], v16 offset:19456
	ds_read_b128 v[162:165], v16 offset:25600
	ds_read_b128 v[166:169], v16 offset:26624
	ds_read_b128 v[170:173], v16 offset:27648
	s_waitcnt lgkmcnt(0)
	v_pk_add_f32 v[128:129], v[128:129], v[150:151]
	v_pk_add_f32 v[154:155], v[154:155], v[158:159]
	v_pk_add_f32 v[130:131], v[130:131], v[152:153]
	v_pk_add_f32 v[156:157], v[156:157], v[160:161]
	v_pk_add_f32 v[128:129], v[128:129], v[154:155]
	v_pk_add_f32 v[130:131], v[130:131], v[156:157]
	v_pk_add_f32 v[132:133], v[132:133], v[162:163]
	v_pk_add_f32 v[166:167], v[166:167], v[170:171]
	v_pk_add_f32 v[134:135], v[134:135], v[164:165]
	v_pk_add_f32 v[168:169], v[168:169], v[172:173]
	v_pk_add_f32 v[132:133], v[132:133], v[166:167]
	v_pk_add_f32 v[134:135], v[134:135], v[168:169]
	v_mul_f32_e32 v176, 0xbfb8aa3b, v128
	v_mul_f32_e32 v177, 0xbfb8aa3b, v129
	v_mul_f32_e32 v178, 0xbfb8aa3b, v130
	v_mul_f32_e32 v179, 0xbfb8aa3b, v131
	v_exp_f32_e32 v176, v176
	v_exp_f32_e32 v177, v177
	v_exp_f32_e32 v178, v178
	v_exp_f32_e32 v179, v179
	s_nop 0
	v_add_f32_e32 v176, 1.0, v176
	v_add_f32_e32 v177, 1.0, v177
	v_add_f32_e32 v178, 1.0, v178
	v_add_f32_e32 v179, 1.0, v179
	v_rcp_f32_e32 v176, v176
	v_rcp_f32_e32 v177, v177
	v_rcp_f32_e32 v178, v178
	v_rcp_f32_e32 v179, v179
	s_nop 0
	v_mul_f32_e32 v176, v128, v176
	v_mul_f32_e32 v177, v129, v177
	v_mul_f32_e32 v178, v130, v178
	v_mul_f32_e32 v179, v131, v179
	v_mul_f32_e32 v176, v176, v132
	v_mul_f32_e32 v177, v177, v133
	v_mul_f32_e32 v178, v178, v134
	v_mul_f32_e32 v179, v179, v135
	v_cvt_pk_bf16_f32 v180, v176, v177
	v_cvt_pk_bf16_f32 v181, v178, v179
	global_store_dwordx2 v[194:195], v[180:181], off
.Lgu_red_done_p8_1:
	s_waitcnt vmcnt(21)
	v_mfma_f32_16x16x32_bf16 v[136:139], v[52:55], v[20:23], 0
	v_mfma_f32_16x16x32_bf16 v[140:143], v[84:87], v[20:23], 0
	s_waitcnt vmcnt(18)
	v_mfma_f32_16x16x32_bf16 v[136:139], v[56:59], v[24:27], v[136:139]
	v_mfma_f32_16x16x32_bf16 v[140:143], v[88:91], v[24:27], v[140:143]
	s_waitcnt vmcnt(15)
	v_mfma_f32_16x16x32_bf16 v[136:139], v[60:63], v[28:31], v[136:139]
	v_mfma_f32_16x16x32_bf16 v[140:143], v[92:95], v[28:31], v[140:143]
	s_waitcnt vmcnt(12)
	v_mfma_f32_16x16x32_bf16 v[136:139], v[64:67], v[32:35], v[136:139]
	v_mfma_f32_16x16x32_bf16 v[140:143], v[96:99], v[32:35], v[140:143]
	s_waitcnt vmcnt(9)
	v_mfma_f32_16x16x32_bf16 v[136:139], v[68:71], v[36:39], v[136:139]
	v_mfma_f32_16x16x32_bf16 v[140:143], v[100:103], v[36:39], v[140:143]
	s_waitcnt vmcnt(6)
	v_mfma_f32_16x16x32_bf16 v[136:139], v[72:75], v[40:43], v[136:139]
	v_mfma_f32_16x16x32_bf16 v[140:143], v[104:107], v[40:43], v[140:143]
	s_waitcnt vmcnt(3)
	v_mfma_f32_16x16x32_bf16 v[136:139], v[76:79], v[44:47], v[136:139]
	v_mfma_f32_16x16x32_bf16 v[140:143], v[108:111], v[44:47], v[140:143]
	s_waitcnt vmcnt(0)
	v_mfma_f32_16x16x32_bf16 v[136:139], v[80:83], v[48:51], v[136:139]
	v_mfma_f32_16x16x32_bf16 v[140:143], v[112:115], v[48:51], v[140:143]
	s_nop 7
	s_nop 1
	ds_write_b128 v16, v[136:139] offset:32768
	ds_write_b128 v16, v[140:143] offset:40960
	s_waitcnt lgkmcnt(0)
	s_barrier
	s_and_b32 s1, s87, 3
	s_cmp_lg_u32 s1, 0
	s_cbranch_scc1 .Lgu_red_done_p8_2
	ds_read_b128 v[150:153], v16 offset:33792
	ds_read_b128 v[154:157], v16 offset:34816
	ds_read_b128 v[158:161], v16 offset:35840
	ds_read_b128 v[162:165], v16 offset:41984
	ds_read_b128 v[166:169], v16 offset:43008
	ds_read_b128 v[170:173], v16 offset:44032
	s_waitcnt lgkmcnt(0)
	v_pk_add_f32 v[136:137], v[136:137], v[150:151]
	v_pk_add_f32 v[154:155], v[154:155], v[158:159]
	v_pk_add_f32 v[138:139], v[138:139], v[152:153]
	v_pk_add_f32 v[156:157], v[156:157], v[160:161]
	v_pk_add_f32 v[136:137], v[136:137], v[154:155]
	v_pk_add_f32 v[138:139], v[138:139], v[156:157]
	v_pk_add_f32 v[140:141], v[140:141], v[162:163]
	v_pk_add_f32 v[166:167], v[166:167], v[170:171]
	v_pk_add_f32 v[142:143], v[142:143], v[164:165]
	v_pk_add_f32 v[168:169], v[168:169], v[172:173]
	v_pk_add_f32 v[140:141], v[140:141], v[166:167]
	v_pk_add_f32 v[142:143], v[142:143], v[168:169]
	v_mul_f32_e32 v176, 0xbfb8aa3b, v136
	v_mul_f32_e32 v177, 0xbfb8aa3b, v137
	v_mul_f32_e32 v178, 0xbfb8aa3b, v138
	v_mul_f32_e32 v179, 0xbfb8aa3b, v139
	v_exp_f32_e32 v176, v176
	v_exp_f32_e32 v177, v177
	v_exp_f32_e32 v178, v178
	v_exp_f32_e32 v179, v179
	s_nop 0
	v_add_f32_e32 v176, 1.0, v176
	v_add_f32_e32 v177, 1.0, v177
	v_add_f32_e32 v178, 1.0, v178
	v_add_f32_e32 v179, 1.0, v179
	v_rcp_f32_e32 v176, v176
	v_rcp_f32_e32 v177, v177
	v_rcp_f32_e32 v178, v178
	v_rcp_f32_e32 v179, v179
	s_nop 0
	v_mul_f32_e32 v176, v136, v176
	v_mul_f32_e32 v177, v137, v177
	v_mul_f32_e32 v178, v138, v178
	v_mul_f32_e32 v179, v139, v179
	v_mul_f32_e32 v176, v176, v140
	v_mul_f32_e32 v177, v177, v141
	v_mul_f32_e32 v178, v178, v142
	v_mul_f32_e32 v179, v179, v143
	v_cvt_pk_bf16_f32 v180, v176, v177
	v_cvt_pk_bf16_f32 v181, v178, v179
	global_store_dwordx2 v[196:197], v[180:181], off

; DI float sigmoidf_(float x) { return __builtin_amdgcn_rcpf(1.0f + __builtin_amdgcn_exp2f(-1.4426950408889634f * x)); }
;     DI void elem2(int row, int col, const f32x4 a, const f32x4 u) const { u32x2 w; w.x = pk2(a[0] * sigmoidf_(a[0]) * u[0], a[1] * sigmoidf_(a[1]) * u[1]); w.y = pk2(a[2] * sigmoidf_(a[2]) * u[2], a[3] * sigmoidf_(a[3]) * u[3]);
;         *(u32x2*)(hact + (size_t)row * FF + col) = w; }
; DI void mini_gemm_gu(const bf16_t* A, const bf16_t* Bt, const EpiGU& E, int bx, int G, int wave, int lane) {
;     const int fr = lane & 15, fq = lane >> 4; const int row = NP + 16 * wave + fr;
;     for (int q = bx; q < FF / 16; q += G) { const int hcol = 16 * q; const int brow = (hcol >> 7) * 256 + (hcol & 127) + fr;
;         const bf16_t* Arow = A + (size_t)row * DM + 8 * fq;
;         f32x4 ga, ua; mini_acc2(Arow, Bt + (size_t)brow * DM + 8 * fq, Bt + (size_t)(brow + 128) * DM + 8 * fq, DM, ga, ua);
;         E.elem2(row, hcol + 4 * fq, ga, ua); }
; }
.Lgu_last_p8:
	s_nop 7
	s_nop 1
	ds_write_b128 v16, v[128:131] offset:16384
	ds_write_b128 v16, v[132:135] offset:24576
	s_waitcnt lgkmcnt(0)
	s_barrier
	s_and_b32 s1, s87, 3
	s_cmp_lg_u32 s1, 0
	s_cbranch_scc1 .Lgu_red_done_p8_1b
	ds_read_b128 v[150:153], v16 offset:17408
	ds_read_b128 v[154:157], v16 offset:18432
	ds_read_b128 v[158:161], v16 offset:19456
	ds_read_b128 v[162:165], v16 offset:25600
	ds_read_b128 v[166:169], v16 offset:26624
	ds_read_b128 v[170:173], v16 offset:27648
	s_waitcnt lgkmcnt(0)
	v_pk_add_f32 v[128:129], v[128:129], v[150:151]
	v_pk_add_f32 v[154:155], v[154:155], v[158:159]
	v_pk_add_f32 v[130:131], v[130:131], v[152:153]
	v_pk_add_f32 v[156:157], v[156:157], v[160:161]
	v_pk_add_f32 v[128:129], v[128:129], v[154:155]
	v_pk_add_f32 v[130:131], v[130:131], v[156:157]
	v_pk_add_f32 v[132:133], v[132:133], v[162:163]
	v_pk_add_f32 v[166:167], v[166:167], v[170:171]
	v_pk_add_f32 v[134:135], v[134:135], v[164:165]
	v_pk_add_f32 v[168:169], v[168:169], v[172:173]
	v_pk_add_f32 v[132:133], v[132:133], v[166:167]
	v_pk_add_f32 v[134:135], v[134:135], v[168:169]
	v_mul_f32_e32 v176, 0xbfb8aa3b, v128
	v_mul_f32_e32 v177, 0xbfb8aa3b, v129
	v_mul_f32_e32 v178, 0xbfb8aa3b, v130
	v_mul_f32_e32 v179, 0xbfb8aa3b, v131
	v_exp_f32_e32 v176, v176
	v_exp_f32_e32 v177, v177
	v_exp_f32_e32 v178, v178
	v_exp_f32_e32 v179, v179
	s_nop 0
	v_add_f32_e32 v176, 1.0, v176
	v_add_f32_e32 v177, 1.0, v177
	v_add_f32_e32 v178, 1.0, v178
	v_add_f32_e32 v179, 1.0, v179
	v_rcp_f32_e32 v176, v176
	v_rcp_f32_e32 v177, v177
	v_rcp_f32_e32 v178, v178
	v_rcp_f32_e32 v179, v179
	s_nop 0
	v_mul_f32_e32 v176, v128, v176
	v_mul_f32_e32 v177, v129, v177
	v_mul_f32_e32 v178, v130, v178
	v_mul_f32_e32 v179, v131, v179
	v_mul_f32_e32 v176, v176, v132
	v_mul_f32_e32 v177, v177, v133
	v_mul_f32_e32 v178, v178, v134
	v_mul_f32_e32 v179, v179, v135
	v_cvt_pk_bf16_f32 v180, v176, v177
	v_cvt_pk_bf16_f32 v181, v178, v179
	global_store_dwordx2 v[194:195], v[180:181], off
.Lgu_red_done_p8_1b:
	s_branch .LBB0_1064
.Lgu_old_p8:
	s_cmpk_gt_i32 s84, 0xaf
	s_cbranch_scc1 .LBB0_1064
	s_lshl_b32 s0, s87, 4
	v_and_b32_e32 v6, 15, v134
	s_add_i32 s0, s0, 0x8000
	v_ashrrev_i32_e32 v7, 4, v134
	v_or_b32_e32 v4, s0, v6
	v_mov_b32_e32 v5, 0
	v_lshlrev_b32_e32 v2, 3, v7
	v_lshlrev_b64 v[0:1], 11, v[4:5]
	v_ashrrev_i32_e32 v3, 31, v2
	s_movk_i32 s0, 0x1600
	v_mov_b64_e32 v[8:9], s[8:9]
	v_lshl_add_u64 v[0:1], s[10:11], 0, v[0:1]
	v_lshlrev_b64 v[2:3], 1, v[2:3]
	v_mad_u64_u32 v[4:5], s[0:1], v4, s0, v[8:9]
	v_lshl_add_u64 v[0:1], v[0:1], 0, v[2:3]
	v_lshl_add_u64 v[2:3], s[4:5], 0, v[2:3]
	v_lshlrev_b32_e32 v7, 2, v7
	s_lshl_b32 s0, s84, 5
	s_lshl_b32 s1, s78, 5
	s_lshl_b32 s2, s84, 4
	s_lshl_b32 s3, s78, 4
	s_mov_b32 s4, s84

;     DI void elem(int row, int col, const f32x4 v) const { u32x2 w; w.x = pk2(v[0], v[1]); w.y = pk2(v[2], v[3]); *(u32x2*)(y + (size_t)row * 1024 + col) = w; }
; DI void mini_acc2(const bf16_t* Arow, const bf16_t* Bg, const bf16_t* Bu, int K, f32x4& ga, f32x4& ua) {
;     ga = (f32x4){0.f, 0.f, 0.f, 0.f}; ua = ga;
;     for (int k0 = 0; k0 < K; k0 += 256) { bf16x8 a[8], g[8], u[8];
; #pragma unroll
;         for (int e = 0; e < 8; ++e) { a[e] = *(const bf16x8*)(Arow + k0 + 32 * e); g[e] = *(const bf16x8*)(Bg + k0 + 32 * e); u[e] = *(const bf16x8*)(Bu + k0 + 32 * e); }
; #pragma unroll
;         for (int e = 0; e < 8; ++e) { ga = __builtin_amdgcn_mfma_f32_16x16x32_bf16(g[e], a[e], ga, 0, 0, 0); ua = __builtin_amdgcn_mfma_f32_16x16x32_bf16(u[e], a[e], ua, 0, 0, 0); } }
; }
; template <class Epi>
; DI void mini_gemm(const bf16_t* A, int lda, const bf16_t* Bt, int ldb, int K, int N, int acol_per_256, const Epi& E, int bx, int G, int wave, int lane) {
;     const int fr = lane & 15, fq = lane >> 4; const int row = NP + 16 * wave + fr;
;     for (int q = bx; q < N / 16; q += G) {
;         const bf16_t* Arow = A + (size_t)row * lda + ((16 * q) >> 8) * acol_per_256 + 8 * fq;
;         const bf16_t* Brow = Bt + (size_t)(16 * q + fr) * ldb + 8 * fq;
;         const f32x4 acc = mini_acc(Arow, Brow, K);
;         E.elem(row, 16 * q + 4 * fq, acc); }
; }
; DI void mini_gemm_gu(const bf16_t* A, const bf16_t* Bt, const EpiGU& E, int bx, int G, int wave, int lane) {
;     const int fr = lane & 15, fq = lane >> 4; const int row = NP + 16 * wave + fr;
;     for (int q = bx; q < FF / 16; q += G) { const int hcol = 16 * q; const int brow = (hcol >> 7) * 256 + (hcol & 127) + fr;
;         const bf16_t* Arow = A + (size_t)row * DM + 8 * fq;
;         f32x4 ga, ua; mini_acc2(Arow, Bt + (size_t)brow * DM + 8 * fq, Bt + (size_t)(brow + 128) * DM + 8 * fq, DM, ga, ua);
;         E.elem2(row, hcol + 4 * fq, ga, ua); }
; }
.LBB0_1796:
	s_cmp_lg_u32 s78, 0x100
	s_cbranch_scc1 .Lgu_old_p16
	v_mbcnt_lo_u32_b32 v0, -1, 0
	v_mbcnt_hi_u32_b32 v0, -1, v0
	v_and_b32_e32 v1, 15, v0
	v_lshrrev_b32_e32 v2, 4, v0
	s_and_b32 s32, s87, 3
	s_lshl_b32 s32, s32, 9
	v_lshl_add_u32 v6, v2, 4, s32
	v_mov_b32_e32 v7, 0
	s_add_u32 s98, s90, 0x4400000
	s_addc_u32 s99, s91, 0
	s_add_u32 s100, s90, 0x1800000
	s_addc_u32 s101, s91, 0
	s_movk_i32 s2, 0x800
	s_lshl_b32 s1, s87, 10
	v_lshl_add_u32 v16, v0, 4, s1
	v_lshl_add_u64 v[14:15], s[98:99], 0, v[6:7]
	v_lshl_add_u64 v[18:19], s[100:101], 0, v[6:7]
	s_add_i32 s3, s84, 0x0
	s_and_b32 s0, s3, 7
	s_lshr_b32 s1, s3, 5
	s_lshl_b32 s1, s1, 3
	s_add_i32 s0, s0, s1
	s_bfe_u32 s1, s3, 0x20003
	s_lshl_b32 s1, s1, 1
	s_lshr_b32 s4, s87, 2
	s_add_i32 s1, s1, s4
	s_lshl_b32 s1, s1, 4
	s_add_i32 s1, s1, 0x8000
	v_add_u32_e32 v3, s1, v1
	s_lshr_b32 s4, s0, 3
	s_lshl_b32 s4, s4, 8
	s_and_b32 s5, s0, 7
	s_lshl_b32 s5, s5, 4
	s_add_i32 s4, s4, s5
	v_add_u32_e32 v4, s4, v1
	v_mad_u64_u32 v[8:9], vcc, v3, s2, v[14:15]
	v_mad_u64_u32 v[10:11], vcc, v4, s2, v[18:19]
	v_add_co_u32_e32 v12, vcc, 0x40000, v10
	s_nop 1
	v_addc_co_u32_e32 v13, vcc, 0, v11, vcc
	global_load_dwordx4 v[20:23], v[8:9], off
	global_load_dwordx4 v[52:55], v[10:11], off
	global_load_dwordx4 v[84:87], v[12:13], off
	global_load_dwordx4 v[24:27], v[8:9], off offset:64
	global_load_dwordx4 v[56:59], v[10:11], off offset:64
	global_load_dwordx4 v[88:91], v[12:13], off offset:64
	global_load_dwordx4 v[28:31], v[8:9], off offset:128
	global_load_dwordx4 v[60:63], v[10:11], off offset:128
	global_load_dwordx4 v[92:95], v[12:13], off offset:128
	global_load_dwordx4 v[32:35], v[8:9], off offset:192
	global_load_dwordx4 v[64:67], v[10:11], off offset:192
	global_load_dwordx4 v[96:99], v[12:13], off offset:192
	global_load_dwordx4 v[36:39], v[8:9], off offset:256
	global_load_dwordx4 v[68:71], v[10:11], off offset:256
	global_load_dwordx4 v[100:103], v[12:13], off offset:256
	global_load_dwordx4 v[40:43], v[8:9], off offset:320
	global_load_dwordx4 v[72:75], v[10:11], off offset:320
	global_load_dwordx4 v[104:107], v[12:13], off offset:320
	global_load_dwordx4 v[44:47], v[8:9], off offset:384
	global_load_dwordx4 v[76:79], v[10:11], off offset:384
	global_load_dwordx4 v[108:111], v[12:13], off offset:384
	global_load_dwordx4 v[48:51], v[8:9], off offset:448
	global_load_dwordx4 v[80:83], v[10:11], off offset:448
	global_load_dwordx4 v[112:115], v[12:13], off offset:448
	v_lshlrev_b32_e32 v192, 3, v2
	s_lshl_b32 s1, s0, 5
	v_add_u32_e32 v192, s1, v192
	v_mov_b32_e32 v193, 0
	s_add_u32 s4, s90, 0x14800000
	s_addc_u32 s5, s91, 0
	v_lshl_add_u64 v[192:193], s[4:5], 0, v[192:193]
	s_movk_i32 s1, 0x1600
	v_mad_u64_u32 v[192:193], vcc, v3, s1, v[192:193]
	s_waitcnt vmcnt(21)
	v_mfma_f32_16x16x32_bf16 v[120:123], v[52:55], v[20:23], 0
	v_mfma_f32_16x16x32_bf16 v[124:127], v[84:87], v[20:23], 0
	s_waitcnt vmcnt(18)
	v_mfma_f32_16x16x32_bf16 v[120:123], v[56:59], v[24:27], v[120:123]
	v_mfma_f32_16x16x32_bf16 v[124:127], v[88:91], v[24:27], v[124:127]
	s_waitcnt vmcnt(15)
	v_mfma_f32_16x16x32_bf16 v[120:123], v[60:63], v[28:31], v[120:123]
	v_mfma_f32_16x16x32_bf16 v[124:127], v[92:95], v[28:31], v[124:127]
	s_waitcnt vmcnt(12)
	v_mfma_f32_16x16x32_bf16 v[120:123], v[64:67], v[32:35], v[120:123]
	v_mfma_f32_16x16x32_bf16 v[124:127], v[96:99], v[32:35], v[124:127]
	s_waitcnt vmcnt(9)
	v_mfma_f32_16x16x32_bf16 v[120:123], v[68:71], v[36:39], v[120:123]
	v_mfma_f32_16x16x32_bf16 v[124:127], v[100:103], v[36:39], v[124:127]
	s_waitcnt vmcnt(6)
	v_mfma_f32_16x16x32_bf16 v[120:123], v[72:75], v[40:43], v[120:123]
	v_mfma_f32_16x16x32_bf16 v[124:127], v[104:107], v[40:43], v[124:127]
	s_waitcnt vmcnt(3)
	v_mfma_f32_16x16x32_bf16 v[120:123], v[76:79], v[44:47], v[120:123]
	v_mfma_f32_16x16x32_bf16 v[124:127], v[108:111], v[44:47], v[124:127]
	s_waitcnt vmcnt(0)
	v_mfma_f32_16x16x32_bf16 v[120:123], v[80:83], v[48:51], v[120:123]
	v_mfma_f32_16x16x32_bf16 v[124:127], v[112:115], v[48:51], v[124:127]
	s_add_i32 s3, s84, 0x100
	s_and_b32 s0, s3, 7
	s_lshr_b32 s1, s3, 5
	s_lshl_b32 s1, s1, 3
	s_add_i32 s0, s0, s1
	s_bfe_u32 s1, s3, 0x20003
	s_lshl_b32 s1, s1, 1
	s_lshr_b32 s4, s87, 2
	s_add_i32 s1, s1, s4
	s_lshl_b32 s1, s1, 4
	s_add_i32 s1, s1, 0x8000
	v_add_u32_e32 v3, s1, v1
	s_lshr_b32 s4, s0, 3
	s_lshl_b32 s4, s4, 8
	s_and_b32 s5, s0, 7
	s_lshl_b32 s5, s5, 4
	s_add_i32 s4, s4, s5
	v_add_u32_e32 v4, s4, v1
	v_mad_u64_u32 v[8:9], vcc, v3, s2, v[14:15]
	v_mad_u64_u32 v[10:11], vcc, v4, s2, v[18:19]
	v_add_co_u32_e32 v12, vcc, 0x40000, v10
	s_nop 1
	v_addc_co_u32_e32 v13, vcc, 0, v11, vcc
	global_load_dwordx4 v[20:23], v[8:9], off
	global_load_dwordx4 v[52:55], v[10:11], off
	global_load_dwordx4 v[84:87], v[12:13], off
	global_load_dwordx4 v[24:27], v[8:9], off offset:64
	global_load_dwordx4 v[56:59], v[10:11], off offset:64
	global_load_dwordx4 v[88:91], v[12:13], off offset:64
	global_load_dwordx4 v[28:31], v[8:9], off offset:128
	global_load_dwordx4 v[60:63], v[10:11], off offset:128
	global_load_dwordx4 v[92:95], v[12:13], off offset:128
	global_load_dwordx4 v[32:35], v[8:9], off offset:192
	global_load_dwordx4 v[64:67], v[10:11], off offset:192
	global_load_dwordx4 v[96:99], v[12:13], off offset:192
	global_load_dwordx4 v[36:39], v[8:9], off offset:256
	global_load_dwordx4 v[68:71], v[10:11], off offset:256
	global_load_dwordx4 v[100:103], v[12:13], off offset:256
	global_load_dwordx4 v[40:43], v[8:9], off offset:320
	global_load_dwordx4 v[72:75], v[10:11], off offset:320
	global_load_dwordx4 v[104:107], v[12:13], off offset:320
	global_load_dwordx4 v[44:47], v[8:9], off offset:384
	global_load_dwordx4 v[76:79], v[10:11], off offset:384
	global_load_dwordx4 v[108:111], v[12:13], off offset:384
	global_load_dwordx4 v[48:51], v[8:9], off offset:448
	global_load_dwordx4 v[80:83], v[10:11], off offset:448
	global_load_dwordx4 v[112:115], v[12:13], off offset:448
	v_lshlrev_b32_e32 v194, 3, v2
	s_lshl_b32 s1, s0, 5
	v_add_u32_e32 v194, s1, v194
	v_mov_b32_e32 v195, 0
	s_add_u32 s4, s90, 0x14800000
	s_addc_u32 s5, s91, 0
	v_lshl_add_u64 v[194:195], s[4:5], 0, v[194:195]
	s_movk_i32 s1, 0x1600
	v_mad_u64_u32 v[194:195], vcc, v3, s1, v[194:195]
	s_nop 7
	s_nop 1
	ds_write_b128 v16, v[120:123] offset:0
	ds_write_b128 v16, v[124:127] offset:8192
	s_waitcnt lgkmcnt(0)
	s_barrier
; DI float sigmoidf_(float x) { return __builtin_amdgcn_rcpf(1.0f + __builtin_amdgcn_exp2f(-1.4426950408889634f * x)); }
;     DI void elem2(int row, int col, const f32x4 a, const f32x4 u) const { u32x2 w; w.x = pk2(a[0] * sigmoidf_(a[0]) * u[0], a[1] * sigmoidf_(a[1]) * u[1]); w.y = pk2(a[2] * sigmoidf_(a[2]) * u[2], a[3] * sigmoidf_(a[3]) * u[3]);
;         *(u32x2*)(hact + (size_t)row * FF + col) = w; }
	s_and_b32 s1, s87, 3
	s_cmp_lg_u32 s1, 0
	s_cbranch_scc1 .Lgu_red_done_p16_0
	ds_read_b128 v[150:153], v16 offset:1024
	ds_read_b128 v[154:157], v16 offset:2048
	ds_read_b128 v[158:161], v16 offset:3072
	ds_read_b128 v[162:165], v16 offset:9216
	ds_read_b128 v[166:169], v16 offset:10240
	ds_read_b128 v[170:173], v16 offset:11264
	s_waitcnt lgkmcnt(0)
	v_pk_add_f32 v[120:121], v[120:121], v[150:151]
	v_pk_add_f32 v[154:155], v[154:155], v[158:159]
	v_pk_add_f32 v[122:123], v[122:123], v[152:153]
	v_pk_add_f32 v[156:157], v[156:157], v[160:161]
	v_pk_add_f32 v[120:121], v[120:121], v[154:155]
	v_pk_add_f32 v[122:123], v[122:123], v[156:157]
	v_pk_add_f32 v[124:125], v[124:125], v[162:163]
	v_pk_add_f32 v[166:167], v[166:167], v[170:171]
	v_pk_add_f32 v[126:127], v[126:127], v[164:165]
	v_pk_add_f32 v[168:169], v[168:169], v[172:173]
	v_pk_add_f32 v[124:125], v[124:125], v[166:167]
	v_pk_add_f32 v[126:127], v[126:127], v[168:169]
	v_mul_f32_e32 v176, 0xbfb8aa3b, v120
	v_mul_f32_e32 v177, 0xbfb8aa3b, v121
	v_mul_f32_e32 v178, 0xbfb8aa3b, v122
	v_mul_f32_e32 v179, 0xbfb8aa3b, v123
	v_exp_f32_e32 v176, v176
	v_exp_f32_e32 v177, v177
	v_exp_f32_e32 v178, v178
	v_exp_f32_e32 v179, v179
	s_nop 0
	v_add_f32_e32 v176, 1.0, v176
	v_add_f32_e32 v177, 1.0, v177
	v_add_f32_e32 v178, 1.0, v178
	v_add_f32_e32 v179, 1.0, v179
	v_rcp_f32_e32 v176, v176
	v_rcp_f32_e32 v177, v177
	v_rcp_f32_e32 v178, v178
	v_rcp_f32_e32 v179, v179
	s_nop 0
	v_mul_f32_e32 v176, v120, v176
	v_mul_f32_e32 v177, v121, v177
	v_mul_f32_e32 v178, v122, v178
	v_mul_f32_e32 v179, v123, v179
	v_mul_f32_e32 v176, v176, v124
	v_mul_f32_e32 v177, v177, v125
	v_mul_f32_e32 v178, v178, v126
	v_mul_f32_e32 v179, v179, v127
	v_cvt_pk_bf16_f32 v180, v176, v177
	v_cvt_pk_bf16_f32 v181, v178, v179
	global_store_dwordx2 v[192:193], v[180:181], off

; DI void mini_gemm_gu(const bf16_t* A, const bf16_t* Bt, const EpiGU& E, int bx, int G, int wave, int lane) {
;     const int fr = lane & 15, fq = lane >> 4; const int row = NP + 16 * wave + fr;
;     for (int q = bx; q < FF / 16; q += G) { const int hcol = 16 * q; const int brow = (hcol >> 7) * 256 + (hcol & 127) + fr;
;         const bf16_t* Arow = A + (size_t)row * DM + 8 * fq;
;         f32x4 ga, ua; mini_acc2(Arow, Bt + (size_t)brow * DM + 8 * fq, Bt + (size_t)(brow + 128) * DM + 8 * fq, DM, ga, ua);
;         E.elem2(row, hcol + 4 * fq, ga, ua); }
; }
.Lgu_red_done_p16_1b:
	s_branch .LBB0_1799
.Lgu_old_p16:
	s_cmpk_gt_i32 s84, 0xaf
	s_cbranch_scc1 .LBB0_1799
	s_lshl_b32 s0, s87, 4
	v_and_b32_e32 v6, 15, v134
	s_add_i32 s0, s0, 0x8000
	v_ashrrev_i32_e32 v7, 4, v134
	v_or_b32_e32 v4, s0, v6
	v_mov_b32_e32 v5, 0
	v_lshlrev_b32_e32 v2, 3, v7
	v_lshlrev_b64 v[0:1], 11, v[4:5]
	v_ashrrev_i32_e32 v3, 31, v2
	s_movk_i32 s0, 0x1600
	v_mov_b64_e32 v[8:9], s[8:9]
	v_lshl_add_u64 v[0:1], s[10:11], 0, v[0:1]
	v_lshlrev_b64 v[2:3], 1, v[2:3]
	v_mad_u64_u32 v[4:5], s[0:1], v4, s0, v[8:9]
	v_lshl_add_u64 v[0:1], v[0:1], 0, v[2:3]
	v_lshl_add_u64 v[2:3], s[4:5], 0, v[2:3]
	v_lshlrev_b32_e32 v7, 2, v7
	s_lshl_b32 s0, s84, 5
	s_lshl_b32 s1, s78, 5
	s_lshl_b32 s2, s84, 4
	s_lshl_b32 s3, s78, 4
	s_mov_b32 s4, s84
